# snake order of the 8 independent MFMAs per k-step in the four GEMM K-loops (each consecutive MFMA changes one operand)
# baseline (speedup 1.0000x reference)
.LBB0_272:
	ds_read_b128 v[146:149], v166
	ds_read_b128 v[150:153], v166 offset:1024
	ds_read_b128 v[154:157], v166 offset:2048
	ds_read_b128 v[170:173], v166 offset:3072
	ds_read_b128 v[174:177], v167
	ds_read_b128 v[178:181], v167 offset:1024
	ds_read_b128 v[182:185], v167 offset:2048
	ds_read_b128 v[186:189], v167 offset:3072
	s_add_u32 s76, s74, 0xfff80080
	s_addc_u32 s77, s75, -1
	s_cmp_eq_u32 s90, 28
	s_cselect_b32 s79, s0, s77
	s_cselect_b32 s78, s1, s76
	s_cselect_b32 s77, s3, s71
	s_cselect_b32 s76, s63, s65
	v_lshl_add_u64 v[158:159], s[74:75], 0, v[138:139]
	s_add_i32 m0, s31, 0xc000
	ds_read_b128 v[190:193], v168
	ds_read_b128 v[194:197], v168 offset:1024
	ds_read_b128 v[198:201], v168 offset:2048
	ds_read_b128 v[202:205], v168 offset:3072
	ds_read_b128 v[206:209], v168 offset:4096
	ds_read_b128 v[214:217], v168 offset:5120
	ds_read_b128 v[218:221], v168 offset:6144
	ds_read_b128 v[222:225], v168 offset:7168
	global_load_lds_dwordx4 v[158:159], off
	v_lshl_add_u64 v[158:159], s[74:75], 0, v[140:141]
	s_add_i32 m0, s31, 0xe000
	s_nop 0
	global_load_lds_dwordx4 v[158:159], off
	s_waitcnt vmcnt(8)
	s_waitcnt lgkmcnt(0)
	s_barrier
	s_setprio 1
	s_waitcnt lgkmcnt(0)
	v_mfma_f32_16x16x32_bf16 v[124:127], v[146:149], v[190:193], v[124:127]
	v_mfma_f32_16x16x32_bf16 v[120:123], v[154:157], v[190:193], v[120:123]
	v_mfma_f32_16x16x32_bf16 v[104:107], v[154:157], v[198:201], v[104:107]
	v_mfma_f32_16x16x32_bf16 v[108:111], v[146:149], v[198:201], v[108:111]
	v_mfma_f32_16x16x32_bf16 v[92:95], v[146:149], v[206:209], v[92:95]
	v_mfma_f32_16x16x32_bf16 v[88:91], v[154:157], v[206:209], v[88:91]
	v_mfma_f32_16x16x32_bf16 v[72:75], v[154:157], v[218:221], v[72:75]
	v_mfma_f32_16x16x32_bf16 v[76:79], v[146:149], v[218:221], v[76:79]
	v_mfma_f32_16x16x32_bf16 v[124:127], v[150:153], v[194:197], v[124:127]
	v_mfma_f32_16x16x32_bf16 v[120:123], v[170:173], v[194:197], v[120:123]
	v_mfma_f32_16x16x32_bf16 v[104:107], v[170:173], v[202:205], v[104:107]
	v_mfma_f32_16x16x32_bf16 v[108:111], v[150:153], v[202:205], v[108:111]
	v_mfma_f32_16x16x32_bf16 v[92:95], v[150:153], v[214:217], v[92:95]
	v_mfma_f32_16x16x32_bf16 v[88:91], v[170:173], v[214:217], v[88:91]
	v_mfma_f32_16x16x32_bf16 v[72:75], v[170:173], v[222:225], v[72:75]
	v_mfma_f32_16x16x32_bf16 v[76:79], v[150:153], v[222:225], v[76:79]
	s_setprio 0
	s_setprio 1
	v_mfma_f32_16x16x32_bf16 v[116:119], v[174:177], v[190:193], v[116:119]
	v_mfma_f32_16x16x32_bf16 v[112:115], v[182:185], v[190:193], v[112:115]
	v_mfma_f32_16x16x32_bf16 v[96:99], v[182:185], v[198:201], v[96:99]
	v_mfma_f32_16x16x32_bf16 v[100:103], v[174:177], v[198:201], v[100:103]
	v_mfma_f32_16x16x32_bf16 v[84:87], v[174:177], v[206:209], v[84:87]
	v_mfma_f32_16x16x32_bf16 v[80:83], v[182:185], v[206:209], v[80:83]
	v_mfma_f32_16x16x32_bf16 v[64:67], v[182:185], v[218:221], v[64:67]
	v_mfma_f32_16x16x32_bf16 v[68:71], v[174:177], v[218:221], v[68:71]
	v_mfma_f32_16x16x32_bf16 v[116:119], v[178:181], v[194:197], v[116:119]
	v_mfma_f32_16x16x32_bf16 v[112:115], v[186:189], v[194:197], v[112:115]
	v_mfma_f32_16x16x32_bf16 v[96:99], v[186:189], v[202:205], v[96:99]
	v_mfma_f32_16x16x32_bf16 v[100:103], v[178:181], v[202:205], v[100:103]
	v_mfma_f32_16x16x32_bf16 v[84:87], v[178:181], v[214:217], v[84:87]
	v_mfma_f32_16x16x32_bf16 v[80:83], v[186:189], v[214:217], v[80:83]
	v_mfma_f32_16x16x32_bf16 v[64:67], v[186:189], v[222:225], v[64:67]
	v_mfma_f32_16x16x32_bf16 v[68:71], v[178:181], v[222:225], v[68:71]
	s_setprio 0
	s_barrier
	s_add_i32 s91, s81, s30
	v_lshl_add_u64 v[158:159], s[76:77], 0, v[130:131]
	s_mov_b32 m0, s91
	ds_read_b128 v[190:193], v168 offset:16384
	ds_read_b128 v[194:197], v168 offset:17408
	ds_read_b128 v[198:201], v168 offset:18432
	ds_read_b128 v[202:205], v168 offset:19456
	ds_read_b128 v[206:209], v168 offset:20480
	ds_read_b128 v[214:217], v168 offset:21504
	ds_read_b128 v[218:221], v168 offset:22528
	ds_read_b128 v[222:225], v168 offset:23552
	global_load_lds_dwordx4 v[158:159], off
	s_add_i32 m0, s91, 0x2000
	s_add_u32 s92, s76, 0x80000
	v_lshl_add_u64 v[210:211], s[76:77], 0, v[134:135]
	s_addc_u32 s93, s77, 0
	s_add_i32 s91, s83, s30
	global_load_lds_dwordx4 v[210:211], off
	v_lshl_add_u64 v[226:227], s[92:93], 0, v[130:131]
	s_mov_b32 m0, s91
	v_lshl_add_u64 v[228:229], s[78:79], 0, v[132:133]
	global_load_lds_dwordx4 v[226:227], off
	v_lshl_add_u64 v[226:227], s[92:93], 0, v[134:135]
	s_add_i32 m0, s91, 0x2000
	s_nop 0
	global_load_lds_dwordx4 v[226:227], off
	v_lshl_add_u64 v[226:227], s[78:79], 0, v[128:129]
	s_mov_b32 m0, s31
	s_nop 0
	global_load_lds_dwordx4 v[226:227], off
	s_mov_b32 m0, s51
	s_nop 0
	global_load_lds_dwordx4 v[228:229], off
	s_waitcnt vmcnt(8)
	s_waitcnt lgkmcnt(0)
	s_barrier
	s_setprio 1
	s_waitcnt lgkmcnt(0)
	v_mfma_f32_16x16x32_bf16 v[60:63], v[146:149], v[190:193], v[60:63]
	v_mfma_f32_16x16x32_bf16 v[56:59], v[154:157], v[190:193], v[56:59]
	v_mfma_f32_16x16x32_bf16 v[40:43], v[154:157], v[198:201], v[40:43]
	v_mfma_f32_16x16x32_bf16 v[44:47], v[146:149], v[198:201], v[44:47]
	v_mfma_f32_16x16x32_bf16 v[28:31], v[146:149], v[206:209], v[28:31]
	v_mfma_f32_16x16x32_bf16 v[24:27], v[154:157], v[206:209], v[24:27]
	v_mfma_f32_16x16x32_bf16 v[8:11], v[154:157], v[218:221], v[8:11]
	v_mfma_f32_16x16x32_bf16 v[12:15], v[146:149], v[218:221], v[12:15]
	v_mfma_f32_16x16x32_bf16 v[60:63], v[150:153], v[194:197], v[60:63]
	v_mfma_f32_16x16x32_bf16 v[56:59], v[170:173], v[194:197], v[56:59]
	v_mfma_f32_16x16x32_bf16 v[40:43], v[170:173], v[202:205], v[40:43]
	v_mfma_f32_16x16x32_bf16 v[44:47], v[150:153], v[202:205], v[44:47]
	v_mfma_f32_16x16x32_bf16 v[28:31], v[150:153], v[214:217], v[28:31]
	v_mfma_f32_16x16x32_bf16 v[24:27], v[170:173], v[214:217], v[24:27]
	v_mfma_f32_16x16x32_bf16 v[8:11], v[170:173], v[222:225], v[8:11]
	v_mfma_f32_16x16x32_bf16 v[12:15], v[150:153], v[222:225], v[12:15]
	s_setprio 0
	s_setprio 1
	v_mfma_f32_16x16x32_bf16 v[52:55], v[174:177], v[190:193], v[52:55]
	v_mfma_f32_16x16x32_bf16 v[48:51], v[182:185], v[190:193], v[48:51]
	v_mfma_f32_16x16x32_bf16 v[32:35], v[182:185], v[198:201], v[32:35]
	v_mfma_f32_16x16x32_bf16 v[36:39], v[174:177], v[198:201], v[36:39]
	v_mfma_f32_16x16x32_bf16 v[20:23], v[174:177], v[206:209], v[20:23]
	v_mfma_f32_16x16x32_bf16 v[16:19], v[182:185], v[206:209], v[16:19]
	v_mfma_f32_16x16x32_bf16 v[0:3], v[182:185], v[218:221], v[0:3]
	v_mfma_f32_16x16x32_bf16 v[4:7], v[174:177], v[218:221], v[4:7]
	v_mfma_f32_16x16x32_bf16 v[52:55], v[178:181], v[194:197], v[52:55]
	v_mfma_f32_16x16x32_bf16 v[48:51], v[186:189], v[194:197], v[48:51]
	v_mfma_f32_16x16x32_bf16 v[32:35], v[186:189], v[202:205], v[32:35]
	v_mfma_f32_16x16x32_bf16 v[36:39], v[178:181], v[202:205], v[36:39]
	v_mfma_f32_16x16x32_bf16 v[20:23], v[178:181], v[214:217], v[20:23]
	v_mfma_f32_16x16x32_bf16 v[16:19], v[186:189], v[214:217], v[16:19]
	v_mfma_f32_16x16x32_bf16 v[0:3], v[186:189], v[222:225], v[0:3]
	v_mfma_f32_16x16x32_bf16 v[4:7], v[178:181], v[222:225], v[4:7]
	s_setprio 0
	s_barrier
	s_add_i32 s91, 0, 0x18000
	v_add_u32_e32 v136, s91, v162
	s_add_i32 s92, 0, 0x1c000
	ds_read_b128 v[146:149], v136
	ds_read_b128 v[150:153], v136 offset:1024
	ds_read_b128 v[154:157], v136 offset:2048
	ds_read_b128 v[170:173], v136 offset:3072
	v_add_u32_e32 v136, s92, v162
	ds_read_b128 v[174:177], v136
	ds_read_b128 v[178:181], v136 offset:1024
	ds_read_b128 v[182:185], v136 offset:2048
	ds_read_b128 v[186:189], v136 offset:3072
	s_add_u32 s78, s78, 0x80000
	s_addc_u32 s79, s79, 0
	s_mov_b32 m0, s28
	v_lshl_add_u64 v[230:231], s[78:79], 0, v[128:129]
	ds_read_b128 v[190:193], v168 offset:32768
	ds_read_b128 v[194:197], v168 offset:33792
	ds_read_b128 v[198:201], v168 offset:34816
	ds_read_b128 v[202:205], v168 offset:35840
	ds_read_b128 v[206:209], v168 offset:36864
	ds_read_b128 v[214:217], v168 offset:37888
	ds_read_b128 v[218:221], v168 offset:38912
	ds_read_b128 v[222:225], v168 offset:39936
	global_load_lds_dwordx4 v[230:231], off
	v_lshl_add_u64 v[230:231], s[78:79], 0, v[132:133]
	s_mov_b32 m0, s29
	s_nop 0
	global_load_lds_dwordx4 v[230:231], off
	s_waitcnt vmcnt(8)
	s_waitcnt lgkmcnt(0)
	s_barrier
	s_setprio 1
	s_waitcnt lgkmcnt(0)
	v_mfma_f32_16x16x32_bf16 v[124:127], v[146:149], v[190:193], v[124:127]
	v_mfma_f32_16x16x32_bf16 v[120:123], v[154:157], v[190:193], v[120:123]
	v_mfma_f32_16x16x32_bf16 v[104:107], v[154:157], v[198:201], v[104:107]
	v_mfma_f32_16x16x32_bf16 v[108:111], v[146:149], v[198:201], v[108:111]
	v_mfma_f32_16x16x32_bf16 v[92:95], v[146:149], v[206:209], v[92:95]
	v_mfma_f32_16x16x32_bf16 v[88:91], v[154:157], v[206:209], v[88:91]
	v_mfma_f32_16x16x32_bf16 v[72:75], v[154:157], v[218:221], v[72:75]
	v_mfma_f32_16x16x32_bf16 v[76:79], v[146:149], v[218:221], v[76:79]
	v_mfma_f32_16x16x32_bf16 v[124:127], v[150:153], v[194:197], v[124:127]
	v_mfma_f32_16x16x32_bf16 v[120:123], v[170:173], v[194:197], v[120:123]
	v_mfma_f32_16x16x32_bf16 v[104:107], v[170:173], v[202:205], v[104:107]
	v_mfma_f32_16x16x32_bf16 v[108:111], v[150:153], v[202:205], v[108:111]
	v_mfma_f32_16x16x32_bf16 v[92:95], v[150:153], v[214:217], v[92:95]
	v_mfma_f32_16x16x32_bf16 v[88:91], v[170:173], v[214:217], v[88:91]
	v_mfma_f32_16x16x32_bf16 v[72:75], v[170:173], v[222:225], v[72:75]
	v_mfma_f32_16x16x32_bf16 v[76:79], v[150:153], v[222:225], v[76:79]
	s_setprio 0
	s_setprio 1
	v_mfma_f32_16x16x32_bf16 v[116:119], v[174:177], v[190:193], v[116:119]
	v_mfma_f32_16x16x32_bf16 v[112:115], v[182:185], v[190:193], v[112:115]
	v_mfma_f32_16x16x32_bf16 v[96:99], v[182:185], v[198:201], v[96:99]
	v_mfma_f32_16x16x32_bf16 v[100:103], v[174:177], v[198:201], v[100:103]
	v_mfma_f32_16x16x32_bf16 v[84:87], v[174:177], v[206:209], v[84:87]
	v_mfma_f32_16x16x32_bf16 v[80:83], v[182:185], v[206:209], v[80:83]
	v_mfma_f32_16x16x32_bf16 v[64:67], v[182:185], v[218:221], v[64:67]
	v_mfma_f32_16x16x32_bf16 v[68:71], v[174:177], v[218:221], v[68:71]
	v_mfma_f32_16x16x32_bf16 v[116:119], v[178:181], v[194:197], v[116:119]
	v_mfma_f32_16x16x32_bf16 v[112:115], v[186:189], v[194:197], v[112:115]
	v_mfma_f32_16x16x32_bf16 v[96:99], v[186:189], v[202:205], v[96:99]
	v_mfma_f32_16x16x32_bf16 v[100:103], v[178:181], v[202:205], v[100:103]
	v_mfma_f32_16x16x32_bf16 v[84:87], v[178:181], v[214:217], v[84:87]
	v_mfma_f32_16x16x32_bf16 v[80:83], v[186:189], v[214:217], v[80:83]
	v_mfma_f32_16x16x32_bf16 v[64:67], v[186:189], v[222:225], v[64:67]
	v_mfma_f32_16x16x32_bf16 v[68:71], v[178:181], v[222:225], v[68:71]
	s_setprio 0
	s_barrier
	s_add_i32 s78, s91, s30
	v_lshl_add_u64 v[158:159], v[158:159], 0, s[34:35]
	s_mov_b32 m0, s78
	ds_read_b128 v[190:193], v168 offset:49152
	ds_read_b128 v[194:197], v168 offset:50176
	ds_read_b128 v[198:201], v168 offset:51200
	ds_read_b128 v[202:205], v168 offset:52224
	ds_read_b128 v[206:209], v168 offset:53248
	ds_read_b128 v[214:217], v168 offset:54272
	ds_read_b128 v[218:221], v168 offset:55296
	ds_read_b128 v[222:225], v168 offset:56320
	global_load_lds_dwordx4 v[158:159], off
	s_add_i32 m0, s78, 0x2000
	s_add_u32 s76, s76, 0x80080
	v_lshl_add_u64 v[158:159], v[210:211], 0, s[34:35]
	s_addc_u32 s77, s77, 0
	s_add_i32 s78, s92, s30
	global_load_lds_dwordx4 v[158:159], off
	v_lshl_add_u64 v[158:159], s[76:77], 0, v[130:131]
	s_mov_b32 m0, s78
	s_nop 0
	global_load_lds_dwordx4 v[158:159], off
	v_lshl_add_u64 v[158:159], s[76:77], 0, v[134:135]
	s_add_i32 m0, s78, 0x2000
	s_nop 0
	global_load_lds_dwordx4 v[158:159], off
	v_lshl_add_u64 v[158:159], v[226:227], 0, s[34:35]
	s_mov_b32 m0, s73
	s_nop 0
	global_load_lds_dwordx4 v[158:159], off
	v_lshl_add_u64 v[158:159], v[228:229], 0, s[34:35]
	s_mov_b32 m0, s80
	s_nop 0
	global_load_lds_dwordx4 v[158:159], off
	s_waitcnt vmcnt(8)
	s_waitcnt lgkmcnt(0)
	s_barrier
	s_setprio 1
	s_waitcnt lgkmcnt(0)
	v_mfma_f32_16x16x32_bf16 v[60:63], v[146:149], v[190:193], v[60:63]
	v_mfma_f32_16x16x32_bf16 v[56:59], v[154:157], v[190:193], v[56:59]
	v_mfma_f32_16x16x32_bf16 v[40:43], v[154:157], v[198:201], v[40:43]
	v_mfma_f32_16x16x32_bf16 v[44:47], v[146:149], v[198:201], v[44:47]
	v_mfma_f32_16x16x32_bf16 v[28:31], v[146:149], v[206:209], v[28:31]
	v_mfma_f32_16x16x32_bf16 v[24:27], v[154:157], v[206:209], v[24:27]
	v_mfma_f32_16x16x32_bf16 v[8:11], v[154:157], v[218:221], v[8:11]
	v_mfma_f32_16x16x32_bf16 v[12:15], v[146:149], v[218:221], v[12:15]
	v_mfma_f32_16x16x32_bf16 v[60:63], v[150:153], v[194:197], v[60:63]
	v_mfma_f32_16x16x32_bf16 v[56:59], v[170:173], v[194:197], v[56:59]
	v_mfma_f32_16x16x32_bf16 v[40:43], v[170:173], v[202:205], v[40:43]
	v_mfma_f32_16x16x32_bf16 v[44:47], v[150:153], v[202:205], v[44:47]
	v_mfma_f32_16x16x32_bf16 v[28:31], v[150:153], v[214:217], v[28:31]
	v_mfma_f32_16x16x32_bf16 v[24:27], v[170:173], v[214:217], v[24:27]
	v_mfma_f32_16x16x32_bf16 v[8:11], v[170:173], v[222:225], v[8:11]
	v_mfma_f32_16x16x32_bf16 v[12:15], v[150:153], v[222:225], v[12:15]
	s_setprio 0
	s_setprio 1
	v_mfma_f32_16x16x32_bf16 v[52:55], v[174:177], v[190:193], v[52:55]
	v_mfma_f32_16x16x32_bf16 v[48:51], v[182:185], v[190:193], v[48:51]
	v_mfma_f32_16x16x32_bf16 v[32:35], v[182:185], v[198:201], v[32:35]
	v_mfma_f32_16x16x32_bf16 v[36:39], v[174:177], v[198:201], v[36:39]
	v_mfma_f32_16x16x32_bf16 v[20:23], v[174:177], v[206:209], v[20:23]
	v_mfma_f32_16x16x32_bf16 v[16:19], v[182:185], v[206:209], v[16:19]
	v_mfma_f32_16x16x32_bf16 v[0:3], v[182:185], v[218:221], v[0:3]
	v_mfma_f32_16x16x32_bf16 v[4:7], v[174:177], v[218:221], v[4:7]
	v_mfma_f32_16x16x32_bf16 v[52:55], v[178:181], v[194:197], v[52:55]
	v_mfma_f32_16x16x32_bf16 v[48:51], v[186:189], v[194:197], v[48:51]
	v_mfma_f32_16x16x32_bf16 v[32:35], v[186:189], v[202:205], v[32:35]
	v_mfma_f32_16x16x32_bf16 v[36:39], v[178:181], v[202:205], v[36:39]
	v_mfma_f32_16x16x32_bf16 v[20:23], v[178:181], v[214:217], v[20:23]
	v_mfma_f32_16x16x32_bf16 v[16:19], v[186:189], v[214:217], v[16:19]
	v_mfma_f32_16x16x32_bf16 v[0:3], v[186:189], v[222:225], v[0:3]
	v_mfma_f32_16x16x32_bf16 v[4:7], v[178:181], v[222:225], v[4:7]
	s_setprio 0
	s_barrier
	s_add_i32 s90, s90, 2
	s_add_u32 s74, s74, 0x100
	s_addc_u32 s75, s75, 0
	s_add_u32 s65, s65, 0x100
	s_addc_u32 s71, s71, 0
	s_cmp_gt_u32 s90, 29
	s_cbranch_scc0 .LBB0_272
	s_and_b64 vcc, exec, s[36:37]
	s_cbranch_vccz .LBB0_275
	s_barrier

.LBB0_543:
	ds_read_b128 v[128:131], v216
	ds_read_b128 v[132:135], v216 offset:1024
	ds_read_b128 v[136:139], v216 offset:2048
	ds_read_b128 v[140:143], v216 offset:3072
	ds_read_b128 v[144:147], v217
	ds_read_b128 v[148:151], v217 offset:1024
	ds_read_b128 v[152:155], v217 offset:2048
	ds_read_b128 v[156:159], v217 offset:3072
	s_add_u32 s44, s42, 0xfff80080
	s_addc_u32 s45, s43, -1
	s_cmp_eq_u32 s58, 28
	s_cselect_b32 s47, s0, s45
	s_cselect_b32 s46, s1, s44
	s_cselect_b32 s45, s3, s35
	s_cselect_b32 s44, s9, s25
	v_lshl_add_u64 v[208:209], s[42:43], 0, v[184:185]
	s_add_i32 m0, s41, 0xc000
	ds_read_b128 v[160:163], v218
	ds_read_b128 v[164:167], v218 offset:1024
	ds_read_b128 v[168:171], v218 offset:2048
	ds_read_b128 v[172:175], v218 offset:3072
	ds_read_b128 v[192:195], v218 offset:4096
	ds_read_b128 v[196:199], v218 offset:5120
	ds_read_b128 v[200:203], v218 offset:6144
	ds_read_b128 v[204:207], v218 offset:7168
	global_load_lds_dwordx4 v[208:209], off
	v_lshl_add_u64 v[208:209], s[42:43], 0, v[186:187]
	s_add_i32 m0, s41, 0xe000
	s_nop 0
	global_load_lds_dwordx4 v[208:209], off
	s_waitcnt vmcnt(8)
	s_waitcnt lgkmcnt(0)
	s_barrier
	s_setprio 1
	s_waitcnt lgkmcnt(0)
	v_mfma_f32_16x16x32_bf16 v[124:127], v[128:131], v[160:163], v[124:127]
	v_mfma_f32_16x16x32_bf16 v[120:123], v[136:139], v[160:163], v[120:123]
	v_mfma_f32_16x16x32_bf16 v[104:107], v[136:139], v[168:171], v[104:107]
	v_mfma_f32_16x16x32_bf16 v[108:111], v[128:131], v[168:171], v[108:111]
	v_mfma_f32_16x16x32_bf16 v[92:95], v[128:131], v[192:195], v[92:95]
	v_mfma_f32_16x16x32_bf16 v[88:91], v[136:139], v[192:195], v[88:91]
	v_mfma_f32_16x16x32_bf16 v[72:75], v[136:139], v[200:203], v[72:75]
	v_mfma_f32_16x16x32_bf16 v[76:79], v[128:131], v[200:203], v[76:79]
	v_mfma_f32_16x16x32_bf16 v[124:127], v[132:135], v[164:167], v[124:127]
	v_mfma_f32_16x16x32_bf16 v[120:123], v[140:143], v[164:167], v[120:123]
	v_mfma_f32_16x16x32_bf16 v[104:107], v[140:143], v[172:175], v[104:107]
	v_mfma_f32_16x16x32_bf16 v[108:111], v[132:135], v[172:175], v[108:111]
	v_mfma_f32_16x16x32_bf16 v[92:95], v[132:135], v[196:199], v[92:95]
	v_mfma_f32_16x16x32_bf16 v[88:91], v[140:143], v[196:199], v[88:91]
	v_mfma_f32_16x16x32_bf16 v[72:75], v[140:143], v[204:207], v[72:75]
	v_mfma_f32_16x16x32_bf16 v[76:79], v[132:135], v[204:207], v[76:79]
	s_setprio 0
	s_setprio 1
	v_mfma_f32_16x16x32_bf16 v[116:119], v[144:147], v[160:163], v[116:119]
	v_mfma_f32_16x16x32_bf16 v[112:115], v[152:155], v[160:163], v[112:115]
	v_mfma_f32_16x16x32_bf16 v[96:99], v[152:155], v[168:171], v[96:99]
	v_mfma_f32_16x16x32_bf16 v[100:103], v[144:147], v[168:171], v[100:103]
	v_mfma_f32_16x16x32_bf16 v[84:87], v[144:147], v[192:195], v[84:87]
	v_mfma_f32_16x16x32_bf16 v[80:83], v[152:155], v[192:195], v[80:83]
	v_mfma_f32_16x16x32_bf16 v[64:67], v[152:155], v[200:203], v[64:67]
	v_mfma_f32_16x16x32_bf16 v[68:71], v[144:147], v[200:203], v[68:71]
	v_mfma_f32_16x16x32_bf16 v[116:119], v[148:151], v[164:167], v[116:119]
	v_mfma_f32_16x16x32_bf16 v[112:115], v[156:159], v[164:167], v[112:115]
	v_mfma_f32_16x16x32_bf16 v[96:99], v[156:159], v[172:175], v[96:99]
	v_mfma_f32_16x16x32_bf16 v[100:103], v[148:151], v[172:175], v[100:103]
	v_mfma_f32_16x16x32_bf16 v[84:87], v[148:151], v[196:199], v[84:87]
	v_mfma_f32_16x16x32_bf16 v[80:83], v[156:159], v[196:199], v[80:83]
	v_mfma_f32_16x16x32_bf16 v[64:67], v[156:159], v[204:207], v[64:67]
	v_mfma_f32_16x16x32_bf16 v[68:71], v[148:151], v[204:207], v[68:71]
	s_setprio 0
	s_barrier
	s_add_i32 s59, s55, s31
	v_lshl_add_u64 v[208:209], s[44:45], 0, v[178:179]
	s_mov_b32 m0, s59
	ds_read_b128 v[160:163], v218 offset:16384
	ds_read_b128 v[164:167], v218 offset:17408
	ds_read_b128 v[168:171], v218 offset:18432
	ds_read_b128 v[172:175], v218 offset:19456
	ds_read_b128 v[192:195], v218 offset:20480
	ds_read_b128 v[196:199], v218 offset:21504
	ds_read_b128 v[200:203], v218 offset:22528
	ds_read_b128 v[204:207], v218 offset:23552
	global_load_lds_dwordx4 v[208:209], off
	s_add_i32 m0, s59, 0x2000
	s_add_u32 s60, s44, 0x80000
	v_lshl_add_u64 v[210:211], s[44:45], 0, v[182:183]
	s_addc_u32 s61, s45, 0
	s_add_i32 s59, s56, s31
	global_load_lds_dwordx4 v[210:211], off
	v_lshl_add_u64 v[222:223], s[60:61], 0, v[178:179]
	s_mov_b32 m0, s59
	v_lshl_add_u64 v[224:225], s[46:47], 0, v[180:181]
	global_load_lds_dwordx4 v[222:223], off
	v_lshl_add_u64 v[222:223], s[60:61], 0, v[182:183]
	s_add_i32 m0, s59, 0x2000
	s_nop 0
	global_load_lds_dwordx4 v[222:223], off
	v_lshl_add_u64 v[222:223], s[46:47], 0, v[176:177]
	s_mov_b32 m0, s41
	s_nop 0
	global_load_lds_dwordx4 v[222:223], off
	s_mov_b32 m0, s48
	s_nop 0
	global_load_lds_dwordx4 v[224:225], off
	s_waitcnt vmcnt(8)
	s_waitcnt lgkmcnt(0)
	s_barrier
	s_setprio 1
	s_waitcnt lgkmcnt(0)
	v_mfma_f32_16x16x32_bf16 v[60:63], v[128:131], v[160:163], v[60:63]
	v_mfma_f32_16x16x32_bf16 v[56:59], v[136:139], v[160:163], v[56:59]
	v_mfma_f32_16x16x32_bf16 v[40:43], v[136:139], v[168:171], v[40:43]
	v_mfma_f32_16x16x32_bf16 v[44:47], v[128:131], v[168:171], v[44:47]
	v_mfma_f32_16x16x32_bf16 v[28:31], v[128:131], v[192:195], v[28:31]
	v_mfma_f32_16x16x32_bf16 v[24:27], v[136:139], v[192:195], v[24:27]
	v_mfma_f32_16x16x32_bf16 v[8:11], v[136:139], v[200:203], v[8:11]
	v_mfma_f32_16x16x32_bf16 v[12:15], v[128:131], v[200:203], v[12:15]
	v_mfma_f32_16x16x32_bf16 v[60:63], v[132:135], v[164:167], v[60:63]
	v_mfma_f32_16x16x32_bf16 v[56:59], v[140:143], v[164:167], v[56:59]
	v_mfma_f32_16x16x32_bf16 v[40:43], v[140:143], v[172:175], v[40:43]
	v_mfma_f32_16x16x32_bf16 v[44:47], v[132:135], v[172:175], v[44:47]
	v_mfma_f32_16x16x32_bf16 v[28:31], v[132:135], v[196:199], v[28:31]
	v_mfma_f32_16x16x32_bf16 v[24:27], v[140:143], v[196:199], v[24:27]
	v_mfma_f32_16x16x32_bf16 v[8:11], v[140:143], v[204:207], v[8:11]
	v_mfma_f32_16x16x32_bf16 v[12:15], v[132:135], v[204:207], v[12:15]
	s_setprio 0
	s_setprio 1
	v_mfma_f32_16x16x32_bf16 v[52:55], v[144:147], v[160:163], v[52:55]
	v_mfma_f32_16x16x32_bf16 v[48:51], v[152:155], v[160:163], v[48:51]
	v_mfma_f32_16x16x32_bf16 v[32:35], v[152:155], v[168:171], v[32:35]
	v_mfma_f32_16x16x32_bf16 v[36:39], v[144:147], v[168:171], v[36:39]
	v_mfma_f32_16x16x32_bf16 v[20:23], v[144:147], v[192:195], v[20:23]
	v_mfma_f32_16x16x32_bf16 v[16:19], v[152:155], v[192:195], v[16:19]
	v_mfma_f32_16x16x32_bf16 v[0:3], v[152:155], v[200:203], v[0:3]
	v_mfma_f32_16x16x32_bf16 v[4:7], v[144:147], v[200:203], v[4:7]
	v_mfma_f32_16x16x32_bf16 v[52:55], v[148:151], v[164:167], v[52:55]
	v_mfma_f32_16x16x32_bf16 v[48:51], v[156:159], v[164:167], v[48:51]
	v_mfma_f32_16x16x32_bf16 v[32:35], v[156:159], v[172:175], v[32:35]
	v_mfma_f32_16x16x32_bf16 v[36:39], v[148:151], v[172:175], v[36:39]
	v_mfma_f32_16x16x32_bf16 v[20:23], v[148:151], v[196:199], v[20:23]
	v_mfma_f32_16x16x32_bf16 v[16:19], v[156:159], v[196:199], v[16:19]
	v_mfma_f32_16x16x32_bf16 v[0:3], v[156:159], v[204:207], v[0:3]
	v_mfma_f32_16x16x32_bf16 v[4:7], v[148:151], v[204:207], v[4:7]
	s_setprio 0
	s_barrier
	s_add_i32 s59, 0, 0x18000
	s_add_i32 s60, 0, 0x1c000
	v_add_u32_e32 v140, s59, v214
	v_add_u32_e32 v156, s60, v214
	ds_read_b128 v[128:131], v140
	ds_read_b128 v[132:135], v140 offset:1024
	ds_read_b128 v[136:139], v140 offset:2048
	ds_read_b128 v[140:143], v140 offset:3072
	ds_read_b128 v[144:147], v156
	ds_read_b128 v[148:151], v156 offset:1024
	ds_read_b128 v[152:155], v156 offset:2048
	ds_read_b128 v[156:159], v156 offset:3072
	s_add_u32 s46, s46, 0x80000
	s_addc_u32 s47, s47, 0
	s_mov_b32 m0, s49
	v_lshl_add_u64 v[226:227], s[46:47], 0, v[176:177]
	ds_read_b128 v[160:163], v218 offset:32768
	ds_read_b128 v[164:167], v218 offset:33792
	ds_read_b128 v[168:171], v218 offset:34816
	ds_read_b128 v[172:175], v218 offset:35840
	ds_read_b128 v[192:195], v218 offset:36864
	ds_read_b128 v[196:199], v218 offset:37888
	ds_read_b128 v[200:203], v218 offset:38912
	ds_read_b128 v[204:207], v218 offset:39936
	global_load_lds_dwordx4 v[226:227], off
	v_lshl_add_u64 v[226:227], s[46:47], 0, v[180:181]
	s_mov_b32 m0, s50
	s_nop 0
	global_load_lds_dwordx4 v[226:227], off
	s_waitcnt vmcnt(8)
	s_waitcnt lgkmcnt(0)
	s_barrier
	s_setprio 1
	s_waitcnt lgkmcnt(0)
	v_mfma_f32_16x16x32_bf16 v[124:127], v[128:131], v[160:163], v[124:127]
	v_mfma_f32_16x16x32_bf16 v[120:123], v[136:139], v[160:163], v[120:123]
	v_mfma_f32_16x16x32_bf16 v[104:107], v[136:139], v[168:171], v[104:107]
	v_mfma_f32_16x16x32_bf16 v[108:111], v[128:131], v[168:171], v[108:111]
	v_mfma_f32_16x16x32_bf16 v[92:95], v[128:131], v[192:195], v[92:95]
	v_mfma_f32_16x16x32_bf16 v[88:91], v[136:139], v[192:195], v[88:91]
	v_mfma_f32_16x16x32_bf16 v[72:75], v[136:139], v[200:203], v[72:75]
	v_mfma_f32_16x16x32_bf16 v[76:79], v[128:131], v[200:203], v[76:79]
	v_mfma_f32_16x16x32_bf16 v[124:127], v[132:135], v[164:167], v[124:127]
	v_mfma_f32_16x16x32_bf16 v[120:123], v[140:143], v[164:167], v[120:123]
	v_mfma_f32_16x16x32_bf16 v[104:107], v[140:143], v[172:175], v[104:107]
	v_mfma_f32_16x16x32_bf16 v[108:111], v[132:135], v[172:175], v[108:111]
	v_mfma_f32_16x16x32_bf16 v[92:95], v[132:135], v[196:199], v[92:95]
	v_mfma_f32_16x16x32_bf16 v[88:91], v[140:143], v[196:199], v[88:91]
	v_mfma_f32_16x16x32_bf16 v[72:75], v[140:143], v[204:207], v[72:75]
	v_mfma_f32_16x16x32_bf16 v[76:79], v[132:135], v[204:207], v[76:79]
	s_setprio 0
	s_setprio 1
	v_mfma_f32_16x16x32_bf16 v[116:119], v[144:147], v[160:163], v[116:119]
	v_mfma_f32_16x16x32_bf16 v[112:115], v[152:155], v[160:163], v[112:115]
	v_mfma_f32_16x16x32_bf16 v[96:99], v[152:155], v[168:171], v[96:99]
	v_mfma_f32_16x16x32_bf16 v[100:103], v[144:147], v[168:171], v[100:103]
	v_mfma_f32_16x16x32_bf16 v[84:87], v[144:147], v[192:195], v[84:87]
	v_mfma_f32_16x16x32_bf16 v[80:83], v[152:155], v[192:195], v[80:83]
	v_mfma_f32_16x16x32_bf16 v[64:67], v[152:155], v[200:203], v[64:67]
	v_mfma_f32_16x16x32_bf16 v[68:71], v[144:147], v[200:203], v[68:71]
	v_mfma_f32_16x16x32_bf16 v[116:119], v[148:151], v[164:167], v[116:119]
	v_mfma_f32_16x16x32_bf16 v[112:115], v[156:159], v[164:167], v[112:115]
	v_mfma_f32_16x16x32_bf16 v[96:99], v[156:159], v[172:175], v[96:99]
	v_mfma_f32_16x16x32_bf16 v[100:103], v[148:151], v[172:175], v[100:103]
	v_mfma_f32_16x16x32_bf16 v[84:87], v[148:151], v[196:199], v[84:87]
	v_mfma_f32_16x16x32_bf16 v[80:83], v[156:159], v[196:199], v[80:83]
	v_mfma_f32_16x16x32_bf16 v[64:67], v[156:159], v[204:207], v[64:67]
	v_mfma_f32_16x16x32_bf16 v[68:71], v[148:151], v[204:207], v[68:71]
	s_setprio 0
	s_barrier
	s_add_i32 s46, s59, s31
	v_lshl_add_u64 v[208:209], v[208:209], 0, s[20:21]
	s_mov_b32 m0, s46
	ds_read_b128 v[160:163], v218 offset:49152
	ds_read_b128 v[164:167], v218 offset:50176
	ds_read_b128 v[168:171], v218 offset:51200
	ds_read_b128 v[172:175], v218 offset:52224
	ds_read_b128 v[192:195], v218 offset:53248
	ds_read_b128 v[196:199], v218 offset:54272
	ds_read_b128 v[200:203], v218 offset:55296
	ds_read_b128 v[204:207], v218 offset:56320
	global_load_lds_dwordx4 v[208:209], off
	s_add_i32 m0, s46, 0x2000
	s_add_u32 s44, s44, 0x80080
	v_lshl_add_u64 v[208:209], v[210:211], 0, s[20:21]
	s_addc_u32 s45, s45, 0
	s_add_i32 s46, s60, s31
	global_load_lds_dwordx4 v[208:209], off
	v_lshl_add_u64 v[208:209], s[44:45], 0, v[178:179]
	s_mov_b32 m0, s46
	s_nop 0
	global_load_lds_dwordx4 v[208:209], off
	v_lshl_add_u64 v[208:209], s[44:45], 0, v[182:183]
	s_add_i32 m0, s46, 0x2000
	s_nop 0
	global_load_lds_dwordx4 v[208:209], off
	v_lshl_add_u64 v[208:209], v[222:223], 0, s[20:21]
	s_mov_b32 m0, s52
	s_nop 0
	global_load_lds_dwordx4 v[208:209], off
	v_lshl_add_u64 v[208:209], v[224:225], 0, s[20:21]
	s_mov_b32 m0, s53
	s_nop 0
	global_load_lds_dwordx4 v[208:209], off
	s_waitcnt vmcnt(8)
	s_waitcnt lgkmcnt(0)
	s_barrier
	s_setprio 1
	s_waitcnt lgkmcnt(0)
	v_mfma_f32_16x16x32_bf16 v[60:63], v[128:131], v[160:163], v[60:63]
	v_mfma_f32_16x16x32_bf16 v[56:59], v[136:139], v[160:163], v[56:59]
	v_mfma_f32_16x16x32_bf16 v[40:43], v[136:139], v[168:171], v[40:43]
	v_mfma_f32_16x16x32_bf16 v[44:47], v[128:131], v[168:171], v[44:47]
	v_mfma_f32_16x16x32_bf16 v[28:31], v[128:131], v[192:195], v[28:31]
	v_mfma_f32_16x16x32_bf16 v[24:27], v[136:139], v[192:195], v[24:27]
	v_mfma_f32_16x16x32_bf16 v[8:11], v[136:139], v[200:203], v[8:11]
	v_mfma_f32_16x16x32_bf16 v[12:15], v[128:131], v[200:203], v[12:15]
	v_mfma_f32_16x16x32_bf16 v[60:63], v[132:135], v[164:167], v[60:63]
	v_mfma_f32_16x16x32_bf16 v[56:59], v[140:143], v[164:167], v[56:59]
	v_mfma_f32_16x16x32_bf16 v[40:43], v[140:143], v[172:175], v[40:43]
	v_mfma_f32_16x16x32_bf16 v[44:47], v[132:135], v[172:175], v[44:47]
	v_mfma_f32_16x16x32_bf16 v[28:31], v[132:135], v[196:199], v[28:31]
	v_mfma_f32_16x16x32_bf16 v[24:27], v[140:143], v[196:199], v[24:27]
	v_mfma_f32_16x16x32_bf16 v[8:11], v[140:143], v[204:207], v[8:11]
	v_mfma_f32_16x16x32_bf16 v[12:15], v[132:135], v[204:207], v[12:15]
	s_setprio 0
	s_setprio 1
	v_mfma_f32_16x16x32_bf16 v[52:55], v[144:147], v[160:163], v[52:55]
	v_mfma_f32_16x16x32_bf16 v[48:51], v[152:155], v[160:163], v[48:51]
	v_mfma_f32_16x16x32_bf16 v[32:35], v[152:155], v[168:171], v[32:35]
	v_mfma_f32_16x16x32_bf16 v[36:39], v[144:147], v[168:171], v[36:39]
	v_mfma_f32_16x16x32_bf16 v[20:23], v[144:147], v[192:195], v[20:23]
	v_mfma_f32_16x16x32_bf16 v[16:19], v[152:155], v[192:195], v[16:19]
	v_mfma_f32_16x16x32_bf16 v[0:3], v[152:155], v[200:203], v[0:3]
	v_mfma_f32_16x16x32_bf16 v[4:7], v[144:147], v[200:203], v[4:7]
	v_mfma_f32_16x16x32_bf16 v[52:55], v[148:151], v[164:167], v[52:55]
	v_mfma_f32_16x16x32_bf16 v[48:51], v[156:159], v[164:167], v[48:51]
	v_mfma_f32_16x16x32_bf16 v[32:35], v[156:159], v[172:175], v[32:35]
	v_mfma_f32_16x16x32_bf16 v[36:39], v[148:151], v[172:175], v[36:39]
	v_mfma_f32_16x16x32_bf16 v[20:23], v[148:151], v[196:199], v[20:23]
	v_mfma_f32_16x16x32_bf16 v[16:19], v[156:159], v[196:199], v[16:19]
	v_mfma_f32_16x16x32_bf16 v[0:3], v[156:159], v[204:207], v[0:3]
	v_mfma_f32_16x16x32_bf16 v[4:7], v[148:151], v[204:207], v[4:7]
	s_setprio 0
	s_barrier
	s_add_i32 s58, s58, 2
	s_add_u32 s42, s42, 0x100
	s_addc_u32 s43, s43, 0
	s_add_u32 s25, s25, 0x100
	s_addc_u32 s35, s35, 0
	s_cmp_gt_u32 s58, 29
	s_cbranch_scc0 .LBB0_543
	s_and_b64 vcc, exec, s[22:23]
	s_cbranch_vccz .LBB0_546
	s_barrier

.LBB0_636:
	ds_read_b128 v[148:151], v197
	ds_read_b128 v[170:173], v197 offset:1024
	ds_read_b128 v[174:177], v197 offset:2048
	ds_read_b128 v[178:181], v197 offset:3072
	ds_read_b128 v[182:185], v198
	ds_read_b128 v[186:189], v198 offset:1024
	ds_read_b128 v[202:205], v198 offset:2048
	ds_read_b128 v[206:209], v198 offset:3072
	s_add_u32 s8, s6, 0xfff80080
	s_addc_u32 s9, s7, -1
	s_cmp_eq_u32 s15, 28
	s_cselect_b32 s11, s69, s9
	s_cselect_b32 s10, s68, s8
	s_cselect_b32 s9, s1, s13
	s_cselect_b32 s8, s3, s12
	v_lshl_add_u64 v[134:135], s[6:7], 0, v[162:163]
	s_add_i32 m0, s72, 0xc000
	ds_read_b128 v[214:217], v199
	ds_read_b128 v[218:221], v199 offset:1024
	ds_read_b128 v[222:225], v199 offset:2048
	ds_read_b128 v[226:229], v199 offset:3072
	ds_read_b128 v[230:233], v199 offset:4096
	ds_read_b128 v[234:237], v199 offset:5120
	ds_read_b128 v[238:241], v199 offset:6144
	ds_read_b128 v[242:245], v199 offset:7168
	global_load_lds_dwordx4 v[134:135], off
	v_lshl_add_u64 v[134:135], s[6:7], 0, v[164:165]
	s_add_i32 m0, s72, 0xe000
	s_nop 0
	global_load_lds_dwordx4 v[134:135], off
	s_waitcnt vmcnt(8)
	s_waitcnt lgkmcnt(0)
	s_barrier
	s_setprio 1
	s_waitcnt lgkmcnt(0)
	v_mfma_f32_16x16x32_bf16 v[112:115], v[148:151], v[214:217], v[112:115]
	v_mfma_f32_16x16x32_bf16 v[80:83], v[174:177], v[214:217], v[80:83]
	v_mfma_f32_16x16x32_bf16 v[88:91], v[174:177], v[222:225], v[88:91]
	v_mfma_f32_16x16x32_bf16 v[116:119], v[148:151], v[222:225], v[116:119]
	v_mfma_f32_16x16x32_bf16 v[124:127], v[148:151], v[230:233], v[124:127]
	v_mfma_f32_16x16x32_bf16 v[92:95], v[174:177], v[230:233], v[92:95]
	v_mfma_f32_16x16x32_bf16 v[84:87], v[174:177], v[238:241], v[84:87]
	v_mfma_f32_16x16x32_bf16 v[120:123], v[148:151], v[238:241], v[120:123]
	v_mfma_f32_16x16x32_bf16 v[112:115], v[170:173], v[218:221], v[112:115]
	v_mfma_f32_16x16x32_bf16 v[80:83], v[178:181], v[218:221], v[80:83]
	v_mfma_f32_16x16x32_bf16 v[88:91], v[178:181], v[226:229], v[88:91]
	v_mfma_f32_16x16x32_bf16 v[116:119], v[170:173], v[226:229], v[116:119]
	v_mfma_f32_16x16x32_bf16 v[124:127], v[170:173], v[234:237], v[124:127]
	v_mfma_f32_16x16x32_bf16 v[92:95], v[178:181], v[234:237], v[92:95]
	v_mfma_f32_16x16x32_bf16 v[84:87], v[178:181], v[242:245], v[84:87]
	v_mfma_f32_16x16x32_bf16 v[120:123], v[170:173], v[242:245], v[120:123]
	s_setprio 0
	s_setprio 1
	v_mfma_f32_16x16x32_bf16 v[108:111], v[182:185], v[214:217], v[108:111]
	v_mfma_f32_16x16x32_bf16 v[76:79], v[202:205], v[214:217], v[76:79]
	v_mfma_f32_16x16x32_bf16 v[72:75], v[202:205], v[222:225], v[72:75]
	v_mfma_f32_16x16x32_bf16 v[104:107], v[182:185], v[222:225], v[104:107]
	v_mfma_f32_16x16x32_bf16 v[100:103], v[182:185], v[230:233], v[100:103]
	v_mfma_f32_16x16x32_bf16 v[68:71], v[202:205], v[230:233], v[68:71]
	v_mfma_f32_16x16x32_bf16 v[64:67], v[202:205], v[238:241], v[64:67]
	v_mfma_f32_16x16x32_bf16 v[96:99], v[182:185], v[238:241], v[96:99]
	v_mfma_f32_16x16x32_bf16 v[108:111], v[186:189], v[218:221], v[108:111]
	v_mfma_f32_16x16x32_bf16 v[76:79], v[206:209], v[218:221], v[76:79]
	v_mfma_f32_16x16x32_bf16 v[72:75], v[206:209], v[226:229], v[72:75]
	v_mfma_f32_16x16x32_bf16 v[104:107], v[186:189], v[226:229], v[104:107]
	v_mfma_f32_16x16x32_bf16 v[100:103], v[186:189], v[234:237], v[100:103]
	v_mfma_f32_16x16x32_bf16 v[68:71], v[206:209], v[234:237], v[68:71]
	v_mfma_f32_16x16x32_bf16 v[64:67], v[206:209], v[242:245], v[64:67]
	v_mfma_f32_16x16x32_bf16 v[96:99], v[186:189], v[242:245], v[96:99]
	s_setprio 0
	s_barrier
	s_add_i32 s16, s94, s63
	v_lshl_add_u64 v[134:135], s[8:9], 0, v[154:155]
	s_mov_b32 m0, s16
	ds_read_b128 v[214:217], v199 offset:16384
	ds_read_b128 v[218:221], v199 offset:17408
	ds_read_b128 v[222:225], v199 offset:18432
	ds_read_b128 v[226:229], v199 offset:19456
	ds_read_b128 v[230:233], v199 offset:20480
	ds_read_b128 v[234:237], v199 offset:21504
	ds_read_b128 v[238:241], v199 offset:22528
	ds_read_b128 v[242:245], v199 offset:23552
	global_load_lds_dwordx4 v[134:135], off
	s_add_i32 m0, s16, 0x2000
	s_add_u32 s16, s8, 0x80000
	v_lshl_add_u64 v[190:191], s[8:9], 0, v[158:159]
	s_addc_u32 s17, s9, 0
	s_add_i32 s18, s95, s63
	global_load_lds_dwordx4 v[190:191], off
	v_lshl_add_u64 v[210:211], s[16:17], 0, v[154:155]
	s_mov_b32 m0, s18
	v_lshl_add_u64 v[246:247], s[10:11], 0, v[156:157]
	global_load_lds_dwordx4 v[210:211], off
	v_lshl_add_u64 v[210:211], s[16:17], 0, v[158:159]
	s_add_i32 m0, s18, 0x2000
	s_nop 0
	global_load_lds_dwordx4 v[210:211], off
	v_lshl_add_u64 v[210:211], s[10:11], 0, v[152:153]
	s_mov_b32 m0, s72
	s_nop 0
	global_load_lds_dwordx4 v[210:211], off
	s_mov_b32 m0, s73
	s_nop 0
	global_load_lds_dwordx4 v[246:247], off
	s_waitcnt vmcnt(8)
	s_waitcnt lgkmcnt(0)
	s_barrier
	s_setprio 1
	s_waitcnt lgkmcnt(0)
	v_mfma_f32_16x16x32_bf16 v[48:51], v[148:151], v[214:217], v[48:51]
	v_mfma_f32_16x16x32_bf16 v[16:19], v[174:177], v[214:217], v[16:19]
	v_mfma_f32_16x16x32_bf16 v[24:27], v[174:177], v[222:225], v[24:27]
	v_mfma_f32_16x16x32_bf16 v[52:55], v[148:151], v[222:225], v[52:55]
	v_mfma_f32_16x16x32_bf16 v[60:63], v[148:151], v[230:233], v[60:63]
	v_mfma_f32_16x16x32_bf16 v[28:31], v[174:177], v[230:233], v[28:31]
	v_mfma_f32_16x16x32_bf16 v[20:23], v[174:177], v[238:241], v[20:23]
	v_mfma_f32_16x16x32_bf16 v[56:59], v[148:151], v[238:241], v[56:59]
	v_mfma_f32_16x16x32_bf16 v[48:51], v[170:173], v[218:221], v[48:51]
	v_mfma_f32_16x16x32_bf16 v[16:19], v[178:181], v[218:221], v[16:19]
	v_mfma_f32_16x16x32_bf16 v[24:27], v[178:181], v[226:229], v[24:27]
	v_mfma_f32_16x16x32_bf16 v[52:55], v[170:173], v[226:229], v[52:55]
	v_mfma_f32_16x16x32_bf16 v[60:63], v[170:173], v[234:237], v[60:63]
	v_mfma_f32_16x16x32_bf16 v[28:31], v[178:181], v[234:237], v[28:31]
	v_mfma_f32_16x16x32_bf16 v[20:23], v[178:181], v[242:245], v[20:23]
	v_mfma_f32_16x16x32_bf16 v[56:59], v[170:173], v[242:245], v[56:59]
	s_setprio 0
	s_setprio 1
	v_mfma_f32_16x16x32_bf16 v[44:47], v[182:185], v[214:217], v[44:47]
	v_mfma_f32_16x16x32_bf16 v[12:15], v[202:205], v[214:217], v[12:15]
	v_mfma_f32_16x16x32_bf16 v[8:11], v[202:205], v[222:225], v[8:11]
	v_mfma_f32_16x16x32_bf16 v[40:43], v[182:185], v[222:225], v[40:43]
	v_mfma_f32_16x16x32_bf16 v[36:39], v[182:185], v[230:233], v[36:39]
	v_mfma_f32_16x16x32_bf16 v[4:7], v[202:205], v[230:233], v[4:7]
	v_mfma_f32_16x16x32_bf16 v[0:3], v[202:205], v[238:241], v[0:3]
	v_mfma_f32_16x16x32_bf16 v[32:35], v[182:185], v[238:241], v[32:35]
	v_mfma_f32_16x16x32_bf16 v[44:47], v[186:189], v[218:221], v[44:47]
	v_mfma_f32_16x16x32_bf16 v[12:15], v[206:209], v[218:221], v[12:15]
	v_mfma_f32_16x16x32_bf16 v[8:11], v[206:209], v[226:229], v[8:11]
	v_mfma_f32_16x16x32_bf16 v[40:43], v[186:189], v[226:229], v[40:43]
	v_mfma_f32_16x16x32_bf16 v[36:39], v[186:189], v[234:237], v[36:39]
	v_mfma_f32_16x16x32_bf16 v[4:7], v[206:209], v[234:237], v[4:7]
	v_mfma_f32_16x16x32_bf16 v[0:3], v[206:209], v[242:245], v[0:3]
	v_mfma_f32_16x16x32_bf16 v[32:35], v[186:189], v[242:245], v[32:35]
	s_setprio 0
	s_barrier
	s_add_i32 s16, 0, 0x18000
	s_add_i32 s17, 0, 0x1c000
	v_add_u32_e32 v178, s16, v196
	v_add_u32_e32 v201, s17, v196
	ds_read_b128 v[148:151], v178
	ds_read_b128 v[170:173], v178 offset:1024
	ds_read_b128 v[174:177], v178 offset:2048
	ds_read_b128 v[178:181], v178 offset:3072
	ds_read_b128 v[182:185], v201
	ds_read_b128 v[186:189], v201 offset:1024
	ds_read_b128 v[202:205], v201 offset:2048
	ds_read_b128 v[206:209], v201 offset:3072
	s_add_u32 s10, s10, 0x80000
	s_addc_u32 s11, s11, 0
	s_mov_b32 m0, s74
	v_lshl_add_u64 v[248:249], s[10:11], 0, v[152:153]
	ds_read_b128 v[214:217], v199 offset:32768
	ds_read_b128 v[218:221], v199 offset:33792
	ds_read_b128 v[222:225], v199 offset:34816
	ds_read_b128 v[226:229], v199 offset:35840
	ds_read_b128 v[230:233], v199 offset:36864
	ds_read_b128 v[234:237], v199 offset:37888
	ds_read_b128 v[238:241], v199 offset:38912
	ds_read_b128 v[242:245], v199 offset:39936
	global_load_lds_dwordx4 v[248:249], off
	v_lshl_add_u64 v[248:249], s[10:11], 0, v[156:157]
	s_mov_b32 m0, s75
	s_nop 0
	global_load_lds_dwordx4 v[248:249], off
	s_waitcnt vmcnt(8)
	s_waitcnt lgkmcnt(0)
	s_barrier
	s_setprio 1
	s_waitcnt lgkmcnt(0)
	v_mfma_f32_16x16x32_bf16 v[112:115], v[148:151], v[214:217], v[112:115]
	v_mfma_f32_16x16x32_bf16 v[80:83], v[174:177], v[214:217], v[80:83]
	v_mfma_f32_16x16x32_bf16 v[88:91], v[174:177], v[222:225], v[88:91]
	v_mfma_f32_16x16x32_bf16 v[116:119], v[148:151], v[222:225], v[116:119]
	v_mfma_f32_16x16x32_bf16 v[124:127], v[148:151], v[230:233], v[124:127]
	v_mfma_f32_16x16x32_bf16 v[92:95], v[174:177], v[230:233], v[92:95]
	v_mfma_f32_16x16x32_bf16 v[84:87], v[174:177], v[238:241], v[84:87]
	v_mfma_f32_16x16x32_bf16 v[120:123], v[148:151], v[238:241], v[120:123]
	v_mfma_f32_16x16x32_bf16 v[112:115], v[170:173], v[218:221], v[112:115]
	v_mfma_f32_16x16x32_bf16 v[80:83], v[178:181], v[218:221], v[80:83]
	v_mfma_f32_16x16x32_bf16 v[88:91], v[178:181], v[226:229], v[88:91]
	v_mfma_f32_16x16x32_bf16 v[116:119], v[170:173], v[226:229], v[116:119]
	v_mfma_f32_16x16x32_bf16 v[124:127], v[170:173], v[234:237], v[124:127]
	v_mfma_f32_16x16x32_bf16 v[92:95], v[178:181], v[234:237], v[92:95]
	v_mfma_f32_16x16x32_bf16 v[84:87], v[178:181], v[242:245], v[84:87]
	v_mfma_f32_16x16x32_bf16 v[120:123], v[170:173], v[242:245], v[120:123]
	s_setprio 0
	s_setprio 1
	v_mfma_f32_16x16x32_bf16 v[108:111], v[182:185], v[214:217], v[108:111]
	v_mfma_f32_16x16x32_bf16 v[76:79], v[202:205], v[214:217], v[76:79]
	v_mfma_f32_16x16x32_bf16 v[72:75], v[202:205], v[222:225], v[72:75]
	v_mfma_f32_16x16x32_bf16 v[104:107], v[182:185], v[222:225], v[104:107]
	v_mfma_f32_16x16x32_bf16 v[100:103], v[182:185], v[230:233], v[100:103]
	v_mfma_f32_16x16x32_bf16 v[68:71], v[202:205], v[230:233], v[68:71]
	v_mfma_f32_16x16x32_bf16 v[64:67], v[202:205], v[238:241], v[64:67]
	v_mfma_f32_16x16x32_bf16 v[96:99], v[182:185], v[238:241], v[96:99]
	v_mfma_f32_16x16x32_bf16 v[108:111], v[186:189], v[218:221], v[108:111]
	v_mfma_f32_16x16x32_bf16 v[76:79], v[206:209], v[218:221], v[76:79]
	v_mfma_f32_16x16x32_bf16 v[72:75], v[206:209], v[226:229], v[72:75]
	v_mfma_f32_16x16x32_bf16 v[104:107], v[186:189], v[226:229], v[104:107]
	v_mfma_f32_16x16x32_bf16 v[100:103], v[186:189], v[234:237], v[100:103]
	v_mfma_f32_16x16x32_bf16 v[68:71], v[206:209], v[234:237], v[68:71]
	v_mfma_f32_16x16x32_bf16 v[64:67], v[206:209], v[242:245], v[64:67]
	v_mfma_f32_16x16x32_bf16 v[96:99], v[186:189], v[242:245], v[96:99]
	s_setprio 0
	s_barrier
	s_add_i32 s10, s16, s63
	v_lshl_add_u64 v[134:135], v[134:135], 0, s[40:41]
	s_mov_b32 m0, s10
	ds_read_b128 v[214:217], v199 offset:49152
	ds_read_b128 v[218:221], v199 offset:50176
	ds_read_b128 v[222:225], v199 offset:51200
	ds_read_b128 v[226:229], v199 offset:52224
	ds_read_b128 v[230:233], v199 offset:53248
	ds_read_b128 v[234:237], v199 offset:54272
	ds_read_b128 v[238:241], v199 offset:55296
	ds_read_b128 v[242:245], v199 offset:56320
	global_load_lds_dwordx4 v[134:135], off
	s_add_i32 m0, s10, 0x2000
	s_add_u32 s8, s8, 0x80080
	v_lshl_add_u64 v[134:135], v[190:191], 0, s[40:41]
	s_addc_u32 s9, s9, 0
	s_add_i32 s10, s17, s63
	global_load_lds_dwordx4 v[134:135], off
	v_lshl_add_u64 v[134:135], s[8:9], 0, v[154:155]
	s_mov_b32 m0, s10
	s_nop 0
	global_load_lds_dwordx4 v[134:135], off
	v_lshl_add_u64 v[134:135], s[8:9], 0, v[158:159]
	s_add_i32 m0, s10, 0x2000
	s_nop 0
	global_load_lds_dwordx4 v[134:135], off
	v_lshl_add_u64 v[134:135], v[210:211], 0, s[40:41]
	s_mov_b32 m0, s82
	s_nop 0
	global_load_lds_dwordx4 v[134:135], off
	v_lshl_add_u64 v[134:135], v[246:247], 0, s[40:41]
	s_mov_b32 m0, s83
	s_nop 0
	global_load_lds_dwordx4 v[134:135], off
	s_waitcnt vmcnt(8)
	s_waitcnt lgkmcnt(0)
	s_barrier
	s_setprio 1
	s_waitcnt lgkmcnt(0)
	v_mfma_f32_16x16x32_bf16 v[48:51], v[148:151], v[214:217], v[48:51]
	v_mfma_f32_16x16x32_bf16 v[16:19], v[174:177], v[214:217], v[16:19]
	v_mfma_f32_16x16x32_bf16 v[24:27], v[174:177], v[222:225], v[24:27]
	v_mfma_f32_16x16x32_bf16 v[52:55], v[148:151], v[222:225], v[52:55]
	v_mfma_f32_16x16x32_bf16 v[60:63], v[148:151], v[230:233], v[60:63]
	v_mfma_f32_16x16x32_bf16 v[28:31], v[174:177], v[230:233], v[28:31]
	v_mfma_f32_16x16x32_bf16 v[20:23], v[174:177], v[238:241], v[20:23]
	v_mfma_f32_16x16x32_bf16 v[56:59], v[148:151], v[238:241], v[56:59]
	v_mfma_f32_16x16x32_bf16 v[48:51], v[170:173], v[218:221], v[48:51]
	v_mfma_f32_16x16x32_bf16 v[16:19], v[178:181], v[218:221], v[16:19]
	v_mfma_f32_16x16x32_bf16 v[24:27], v[178:181], v[226:229], v[24:27]
	v_mfma_f32_16x16x32_bf16 v[52:55], v[170:173], v[226:229], v[52:55]
	v_mfma_f32_16x16x32_bf16 v[60:63], v[170:173], v[234:237], v[60:63]
	v_mfma_f32_16x16x32_bf16 v[28:31], v[178:181], v[234:237], v[28:31]
	v_mfma_f32_16x16x32_bf16 v[20:23], v[178:181], v[242:245], v[20:23]
	v_mfma_f32_16x16x32_bf16 v[56:59], v[170:173], v[242:245], v[56:59]
	s_setprio 0
	s_setprio 1
	v_mfma_f32_16x16x32_bf16 v[44:47], v[182:185], v[214:217], v[44:47]
	v_mfma_f32_16x16x32_bf16 v[12:15], v[202:205], v[214:217], v[12:15]
	v_mfma_f32_16x16x32_bf16 v[8:11], v[202:205], v[222:225], v[8:11]
	v_mfma_f32_16x16x32_bf16 v[40:43], v[182:185], v[222:225], v[40:43]
	v_mfma_f32_16x16x32_bf16 v[36:39], v[182:185], v[230:233], v[36:39]
	v_mfma_f32_16x16x32_bf16 v[4:7], v[202:205], v[230:233], v[4:7]
	v_mfma_f32_16x16x32_bf16 v[0:3], v[202:205], v[238:241], v[0:3]
	v_mfma_f32_16x16x32_bf16 v[32:35], v[182:185], v[238:241], v[32:35]
	v_mfma_f32_16x16x32_bf16 v[44:47], v[186:189], v[218:221], v[44:47]
	v_mfma_f32_16x16x32_bf16 v[12:15], v[206:209], v[218:221], v[12:15]
	v_mfma_f32_16x16x32_bf16 v[8:11], v[206:209], v[226:229], v[8:11]
	v_mfma_f32_16x16x32_bf16 v[40:43], v[186:189], v[226:229], v[40:43]
	v_mfma_f32_16x16x32_bf16 v[36:39], v[186:189], v[234:237], v[36:39]
	v_mfma_f32_16x16x32_bf16 v[4:7], v[206:209], v[234:237], v[4:7]
	v_mfma_f32_16x16x32_bf16 v[0:3], v[206:209], v[242:245], v[0:3]
	v_mfma_f32_16x16x32_bf16 v[32:35], v[186:189], v[242:245], v[32:35]
	s_setprio 0
	s_barrier
	s_add_i32 s15, s15, 2
	s_add_u32 s6, s6, 0x100
	s_addc_u32 s7, s7, 0
	s_add_u32 s12, s12, 0x100
	s_addc_u32 s13, s13, 0
	s_cmp_gt_u32 s15, 29
	s_cbranch_scc0 .LBB0_636
	s_and_b64 vcc, exec, s[42:43]
	s_cbranch_vccz .LBB0_639
	s_barrier

.LBB0_876:
	ds_read_b128 v[128:131], v188
	ds_read_b128 v[132:135], v188 offset:1024
	ds_read_b128 v[136:139], v188 offset:2048
	ds_read_b128 v[140:143], v188 offset:3072
	ds_read_b128 v[144:147], v189
	ds_read_b128 v[148:151], v189 offset:1024
	ds_read_b128 v[166:169], v189 offset:2048
	ds_read_b128 v[170:173], v189 offset:3072
	s_add_u32 s40, s38, 0x100
	s_addc_u32 s41, s39, 0
	s_cmpk_eq_i32 s1, 0x52
	s_cselect_b32 s45, s37, s41
	s_cselect_b32 s44, s36, s40
	s_cselect_b32 s43, s17, s5
	s_cselect_b32 s42, s16, s4
	v_lshl_add_u64 v[182:183], s[38:39], 0, v[160:161]
	s_add_i32 m0, s48, 0xc000
	ds_read_b128 v[174:177], v190
	ds_read_b128 v[178:181], v190 offset:1024
	ds_read_b128 v[194:197], v190 offset:2048
	ds_read_b128 v[198:201], v190 offset:3072
	ds_read_b128 v[202:205], v190 offset:4096
	ds_read_b128 v[206:209], v190 offset:5120
	ds_read_b128 v[210:213], v190 offset:6144
	ds_read_b128 v[214:217], v190 offset:7168
	global_load_lds_dwordx4 v[182:183], off
	v_lshl_add_u64 v[182:183], s[38:39], 0, v[162:163]
	s_add_i32 m0, s48, 0xe000
	s_nop 0
	global_load_lds_dwordx4 v[182:183], off
	s_waitcnt vmcnt(8)
	s_waitcnt lgkmcnt(0)
	s_barrier
	s_setprio 1
	s_waitcnt lgkmcnt(0)
	v_mfma_f32_16x16x32_bf16 v[124:127], v[128:131], v[174:177], v[124:127]
	v_mfma_f32_16x16x32_bf16 v[120:123], v[136:139], v[174:177], v[120:123]
	v_mfma_f32_16x16x32_bf16 v[104:107], v[136:139], v[194:197], v[104:107]
	v_mfma_f32_16x16x32_bf16 v[108:111], v[128:131], v[194:197], v[108:111]
	v_mfma_f32_16x16x32_bf16 v[92:95], v[128:131], v[202:205], v[92:95]
	v_mfma_f32_16x16x32_bf16 v[88:91], v[136:139], v[202:205], v[88:91]
	v_mfma_f32_16x16x32_bf16 v[72:75], v[136:139], v[210:213], v[72:75]
	v_mfma_f32_16x16x32_bf16 v[76:79], v[128:131], v[210:213], v[76:79]
	v_mfma_f32_16x16x32_bf16 v[124:127], v[132:135], v[178:181], v[124:127]
	v_mfma_f32_16x16x32_bf16 v[120:123], v[140:143], v[178:181], v[120:123]
	v_mfma_f32_16x16x32_bf16 v[104:107], v[140:143], v[198:201], v[104:107]
	v_mfma_f32_16x16x32_bf16 v[108:111], v[132:135], v[198:201], v[108:111]
	v_mfma_f32_16x16x32_bf16 v[92:95], v[132:135], v[206:209], v[92:95]
	v_mfma_f32_16x16x32_bf16 v[88:91], v[140:143], v[206:209], v[88:91]
	v_mfma_f32_16x16x32_bf16 v[72:75], v[140:143], v[214:217], v[72:75]
	v_mfma_f32_16x16x32_bf16 v[76:79], v[132:135], v[214:217], v[76:79]
	s_setprio 0
	s_setprio 1
	v_mfma_f32_16x16x32_bf16 v[116:119], v[144:147], v[174:177], v[116:119]
	v_mfma_f32_16x16x32_bf16 v[112:115], v[166:169], v[174:177], v[112:115]
	v_mfma_f32_16x16x32_bf16 v[96:99], v[166:169], v[194:197], v[96:99]
	v_mfma_f32_16x16x32_bf16 v[100:103], v[144:147], v[194:197], v[100:103]
	v_mfma_f32_16x16x32_bf16 v[84:87], v[144:147], v[202:205], v[84:87]
	v_mfma_f32_16x16x32_bf16 v[80:83], v[166:169], v[202:205], v[80:83]
	v_mfma_f32_16x16x32_bf16 v[64:67], v[166:169], v[210:213], v[64:67]
	v_mfma_f32_16x16x32_bf16 v[68:71], v[144:147], v[210:213], v[68:71]
	v_mfma_f32_16x16x32_bf16 v[116:119], v[148:151], v[178:181], v[116:119]
	v_mfma_f32_16x16x32_bf16 v[112:115], v[170:173], v[178:181], v[112:115]
	v_mfma_f32_16x16x32_bf16 v[96:99], v[170:173], v[198:201], v[96:99]
	v_mfma_f32_16x16x32_bf16 v[100:103], v[148:151], v[198:201], v[100:103]
	v_mfma_f32_16x16x32_bf16 v[84:87], v[148:151], v[206:209], v[84:87]
	v_mfma_f32_16x16x32_bf16 v[80:83], v[170:173], v[206:209], v[80:83]
	v_mfma_f32_16x16x32_bf16 v[64:67], v[170:173], v[214:217], v[64:67]
	v_mfma_f32_16x16x32_bf16 v[68:71], v[148:151], v[214:217], v[68:71]
	s_setprio 0
	s_barrier
	s_add_i32 s3, s70, s33
	v_lshl_add_u64 v[182:183], s[42:43], 0, v[154:155]
	s_mov_b32 m0, s3
	ds_read_b128 v[174:177], v190 offset:16384
	ds_read_b128 v[178:181], v190 offset:17408
	ds_read_b128 v[194:197], v190 offset:18432
	ds_read_b128 v[198:201], v190 offset:19456
	ds_read_b128 v[202:205], v190 offset:20480
	ds_read_b128 v[206:209], v190 offset:21504
	ds_read_b128 v[210:213], v190 offset:22528
	ds_read_b128 v[214:217], v190 offset:23552
	global_load_lds_dwordx4 v[182:183], off
	s_add_i32 m0, s3, 0x2000
	s_add_u32 s38, s42, 0x158000
	v_lshl_add_u64 v[218:219], s[42:43], 0, v[158:159]
	s_addc_u32 s39, s43, 0
	s_add_i32 s3, s71, s33
	global_load_lds_dwordx4 v[218:219], off
	v_lshl_add_u64 v[220:221], s[38:39], 0, v[154:155]
	s_mov_b32 m0, s3
	v_lshl_add_u64 v[222:223], s[44:45], 0, v[156:157]
	global_load_lds_dwordx4 v[220:221], off
	v_lshl_add_u64 v[220:221], s[38:39], 0, v[158:159]
	s_add_i32 m0, s3, 0x2000
	s_nop 0
	global_load_lds_dwordx4 v[220:221], off
	v_lshl_add_u64 v[220:221], s[44:45], 0, v[152:153]
	s_mov_b32 m0, s48
	s_nop 0
	global_load_lds_dwordx4 v[220:221], off
	s_mov_b32 m0, s49
	s_nop 0
	global_load_lds_dwordx4 v[222:223], off
	s_waitcnt vmcnt(8)
	s_waitcnt lgkmcnt(0)
	s_barrier
	s_setprio 1
	s_waitcnt lgkmcnt(0)
	v_mfma_f32_16x16x32_bf16 v[60:63], v[128:131], v[174:177], v[60:63]
	v_mfma_f32_16x16x32_bf16 v[56:59], v[136:139], v[174:177], v[56:59]
	v_mfma_f32_16x16x32_bf16 v[40:43], v[136:139], v[194:197], v[40:43]
	v_mfma_f32_16x16x32_bf16 v[44:47], v[128:131], v[194:197], v[44:47]
	v_mfma_f32_16x16x32_bf16 v[28:31], v[128:131], v[202:205], v[28:31]
	v_mfma_f32_16x16x32_bf16 v[24:27], v[136:139], v[202:205], v[24:27]
	v_mfma_f32_16x16x32_bf16 v[8:11], v[136:139], v[210:213], v[8:11]
	v_mfma_f32_16x16x32_bf16 v[12:15], v[128:131], v[210:213], v[12:15]
	v_mfma_f32_16x16x32_bf16 v[60:63], v[132:135], v[178:181], v[60:63]
	v_mfma_f32_16x16x32_bf16 v[56:59], v[140:143], v[178:181], v[56:59]
	v_mfma_f32_16x16x32_bf16 v[40:43], v[140:143], v[198:201], v[40:43]
	v_mfma_f32_16x16x32_bf16 v[44:47], v[132:135], v[198:201], v[44:47]
	v_mfma_f32_16x16x32_bf16 v[28:31], v[132:135], v[206:209], v[28:31]
	v_mfma_f32_16x16x32_bf16 v[24:27], v[140:143], v[206:209], v[24:27]
	v_mfma_f32_16x16x32_bf16 v[8:11], v[140:143], v[214:217], v[8:11]
	v_mfma_f32_16x16x32_bf16 v[12:15], v[132:135], v[214:217], v[12:15]
	s_setprio 0
	s_setprio 1
	v_mfma_f32_16x16x32_bf16 v[52:55], v[144:147], v[174:177], v[52:55]
	v_mfma_f32_16x16x32_bf16 v[48:51], v[166:169], v[174:177], v[48:51]
	v_mfma_f32_16x16x32_bf16 v[32:35], v[166:169], v[194:197], v[32:35]
	v_mfma_f32_16x16x32_bf16 v[36:39], v[144:147], v[194:197], v[36:39]
	v_mfma_f32_16x16x32_bf16 v[20:23], v[144:147], v[202:205], v[20:23]
	v_mfma_f32_16x16x32_bf16 v[16:19], v[166:169], v[202:205], v[16:19]
	v_mfma_f32_16x16x32_bf16 v[0:3], v[166:169], v[210:213], v[0:3]
	v_mfma_f32_16x16x32_bf16 v[4:7], v[144:147], v[210:213], v[4:7]
	v_mfma_f32_16x16x32_bf16 v[52:55], v[148:151], v[178:181], v[52:55]
	v_mfma_f32_16x16x32_bf16 v[48:51], v[170:173], v[178:181], v[48:51]
	v_mfma_f32_16x16x32_bf16 v[32:35], v[170:173], v[198:201], v[32:35]
	v_mfma_f32_16x16x32_bf16 v[36:39], v[148:151], v[198:201], v[36:39]
	v_mfma_f32_16x16x32_bf16 v[20:23], v[148:151], v[206:209], v[20:23]
	v_mfma_f32_16x16x32_bf16 v[16:19], v[170:173], v[206:209], v[16:19]
	v_mfma_f32_16x16x32_bf16 v[0:3], v[170:173], v[214:217], v[0:3]
	v_mfma_f32_16x16x32_bf16 v[4:7], v[148:151], v[214:217], v[4:7]
	s_setprio 0
	s_barrier
	s_add_i32 s3, 0, 0x18000
	s_add_i32 s73, 0, 0x1c000
	v_add_u32_e32 v140, s3, v187
	v_add_u32_e32 v170, s73, v187
	ds_read_b128 v[128:131], v140
	ds_read_b128 v[132:135], v140 offset:1024
	ds_read_b128 v[136:139], v140 offset:2048
	ds_read_b128 v[140:143], v140 offset:3072
	ds_read_b128 v[144:147], v170
	ds_read_b128 v[148:151], v170 offset:1024
	ds_read_b128 v[166:169], v170 offset:2048
	ds_read_b128 v[170:173], v170 offset:3072
	s_add_u32 s38, s44, 0x158000
	s_addc_u32 s39, s45, 0
	s_mov_b32 m0, s51
	v_lshl_add_u64 v[224:225], s[38:39], 0, v[152:153]
	ds_read_b128 v[174:177], v190 offset:32768
	ds_read_b128 v[178:181], v190 offset:33792
	ds_read_b128 v[194:197], v190 offset:34816
	ds_read_b128 v[198:201], v190 offset:35840
	ds_read_b128 v[202:205], v190 offset:36864
	ds_read_b128 v[206:209], v190 offset:37888
	ds_read_b128 v[210:213], v190 offset:38912
	ds_read_b128 v[214:217], v190 offset:39936
	global_load_lds_dwordx4 v[224:225], off
	v_lshl_add_u64 v[224:225], s[38:39], 0, v[156:157]
	s_mov_b32 m0, s52
	s_nop 0
	global_load_lds_dwordx4 v[224:225], off
	s_waitcnt vmcnt(8)
	s_waitcnt lgkmcnt(0)
	s_barrier
	s_setprio 1
	s_waitcnt lgkmcnt(0)
	v_mfma_f32_16x16x32_bf16 v[124:127], v[128:131], v[174:177], v[124:127]
	v_mfma_f32_16x16x32_bf16 v[120:123], v[136:139], v[174:177], v[120:123]
	v_mfma_f32_16x16x32_bf16 v[104:107], v[136:139], v[194:197], v[104:107]
	v_mfma_f32_16x16x32_bf16 v[108:111], v[128:131], v[194:197], v[108:111]
	v_mfma_f32_16x16x32_bf16 v[92:95], v[128:131], v[202:205], v[92:95]
	v_mfma_f32_16x16x32_bf16 v[88:91], v[136:139], v[202:205], v[88:91]
	v_mfma_f32_16x16x32_bf16 v[72:75], v[136:139], v[210:213], v[72:75]
	v_mfma_f32_16x16x32_bf16 v[76:79], v[128:131], v[210:213], v[76:79]
	v_mfma_f32_16x16x32_bf16 v[124:127], v[132:135], v[178:181], v[124:127]
	v_mfma_f32_16x16x32_bf16 v[120:123], v[140:143], v[178:181], v[120:123]
	v_mfma_f32_16x16x32_bf16 v[104:107], v[140:143], v[198:201], v[104:107]
	v_mfma_f32_16x16x32_bf16 v[108:111], v[132:135], v[198:201], v[108:111]
	v_mfma_f32_16x16x32_bf16 v[92:95], v[132:135], v[206:209], v[92:95]
	v_mfma_f32_16x16x32_bf16 v[88:91], v[140:143], v[206:209], v[88:91]
	v_mfma_f32_16x16x32_bf16 v[72:75], v[140:143], v[214:217], v[72:75]
	v_mfma_f32_16x16x32_bf16 v[76:79], v[132:135], v[214:217], v[76:79]
	s_setprio 0
	s_setprio 1
	v_mfma_f32_16x16x32_bf16 v[116:119], v[144:147], v[174:177], v[116:119]
	v_mfma_f32_16x16x32_bf16 v[112:115], v[166:169], v[174:177], v[112:115]
	v_mfma_f32_16x16x32_bf16 v[96:99], v[166:169], v[194:197], v[96:99]
	v_mfma_f32_16x16x32_bf16 v[100:103], v[144:147], v[194:197], v[100:103]
	v_mfma_f32_16x16x32_bf16 v[84:87], v[144:147], v[202:205], v[84:87]
	v_mfma_f32_16x16x32_bf16 v[80:83], v[166:169], v[202:205], v[80:83]
	v_mfma_f32_16x16x32_bf16 v[64:67], v[166:169], v[210:213], v[64:67]
	v_mfma_f32_16x16x32_bf16 v[68:71], v[144:147], v[210:213], v[68:71]
	v_mfma_f32_16x16x32_bf16 v[116:119], v[148:151], v[178:181], v[116:119]
	v_mfma_f32_16x16x32_bf16 v[112:115], v[170:173], v[178:181], v[112:115]
	v_mfma_f32_16x16x32_bf16 v[96:99], v[170:173], v[198:201], v[96:99]
	v_mfma_f32_16x16x32_bf16 v[100:103], v[148:151], v[198:201], v[100:103]
	v_mfma_f32_16x16x32_bf16 v[84:87], v[148:151], v[206:209], v[84:87]
	v_mfma_f32_16x16x32_bf16 v[80:83], v[170:173], v[206:209], v[80:83]
	v_mfma_f32_16x16x32_bf16 v[64:67], v[170:173], v[214:217], v[64:67]
	v_mfma_f32_16x16x32_bf16 v[68:71], v[148:151], v[214:217], v[68:71]
	s_setprio 0
	s_barrier
	s_add_i32 s3, s3, s33
	v_lshl_add_u64 v[182:183], v[182:183], 0, s[24:25]
	s_mov_b32 m0, s3
	ds_read_b128 v[174:177], v190 offset:49152
	ds_read_b128 v[178:181], v190 offset:50176
	ds_read_b128 v[194:197], v190 offset:51200
	ds_read_b128 v[198:201], v190 offset:52224
	ds_read_b128 v[202:205], v190 offset:53248
	ds_read_b128 v[206:209], v190 offset:54272
	ds_read_b128 v[210:213], v190 offset:55296
	ds_read_b128 v[214:217], v190 offset:56320
	global_load_lds_dwordx4 v[182:183], off
	s_add_i32 m0, s3, 0x2000
	s_add_u32 s38, s42, 0x158080
	v_lshl_add_u64 v[182:183], v[218:219], 0, s[24:25]
	s_addc_u32 s39, s43, 0
	s_add_i32 s3, s73, s33
	global_load_lds_dwordx4 v[182:183], off
	v_lshl_add_u64 v[182:183], s[38:39], 0, v[154:155]
	s_mov_b32 m0, s3
	s_nop 0
	global_load_lds_dwordx4 v[182:183], off
	v_lshl_add_u64 v[182:183], s[38:39], 0, v[158:159]
	s_add_i32 m0, s3, 0x2000
	s_nop 0
	global_load_lds_dwordx4 v[182:183], off
	v_lshl_add_u64 v[182:183], v[220:221], 0, s[24:25]
	s_mov_b32 m0, s56
	s_nop 0
	global_load_lds_dwordx4 v[182:183], off
	v_lshl_add_u64 v[182:183], v[222:223], 0, s[24:25]
	s_mov_b32 m0, s57
	s_nop 0
	global_load_lds_dwordx4 v[182:183], off
	s_waitcnt vmcnt(8)
	s_waitcnt lgkmcnt(0)
	s_barrier
	s_setprio 1
	s_waitcnt lgkmcnt(0)
	v_mfma_f32_16x16x32_bf16 v[60:63], v[128:131], v[174:177], v[60:63]
	v_mfma_f32_16x16x32_bf16 v[56:59], v[136:139], v[174:177], v[56:59]
	v_mfma_f32_16x16x32_bf16 v[40:43], v[136:139], v[194:197], v[40:43]
	v_mfma_f32_16x16x32_bf16 v[44:47], v[128:131], v[194:197], v[44:47]
	v_mfma_f32_16x16x32_bf16 v[28:31], v[128:131], v[202:205], v[28:31]
	v_mfma_f32_16x16x32_bf16 v[24:27], v[136:139], v[202:205], v[24:27]
	v_mfma_f32_16x16x32_bf16 v[8:11], v[136:139], v[210:213], v[8:11]
	v_mfma_f32_16x16x32_bf16 v[12:15], v[128:131], v[210:213], v[12:15]
	v_mfma_f32_16x16x32_bf16 v[60:63], v[132:135], v[178:181], v[60:63]
	v_mfma_f32_16x16x32_bf16 v[56:59], v[140:143], v[178:181], v[56:59]
	v_mfma_f32_16x16x32_bf16 v[40:43], v[140:143], v[198:201], v[40:43]
	v_mfma_f32_16x16x32_bf16 v[44:47], v[132:135], v[198:201], v[44:47]
	v_mfma_f32_16x16x32_bf16 v[28:31], v[132:135], v[206:209], v[28:31]
	v_mfma_f32_16x16x32_bf16 v[24:27], v[140:143], v[206:209], v[24:27]
	v_mfma_f32_16x16x32_bf16 v[8:11], v[140:143], v[214:217], v[8:11]
	v_mfma_f32_16x16x32_bf16 v[12:15], v[132:135], v[214:217], v[12:15]
	s_setprio 0
	s_setprio 1
	v_mfma_f32_16x16x32_bf16 v[52:55], v[144:147], v[174:177], v[52:55]
	v_mfma_f32_16x16x32_bf16 v[48:51], v[166:169], v[174:177], v[48:51]
	v_mfma_f32_16x16x32_bf16 v[32:35], v[166:169], v[194:197], v[32:35]
	v_mfma_f32_16x16x32_bf16 v[36:39], v[144:147], v[194:197], v[36:39]
	v_mfma_f32_16x16x32_bf16 v[20:23], v[144:147], v[202:205], v[20:23]
	v_mfma_f32_16x16x32_bf16 v[16:19], v[166:169], v[202:205], v[16:19]
	v_mfma_f32_16x16x32_bf16 v[0:3], v[166:169], v[210:213], v[0:3]
	v_mfma_f32_16x16x32_bf16 v[4:7], v[144:147], v[210:213], v[4:7]
	v_mfma_f32_16x16x32_bf16 v[52:55], v[148:151], v[178:181], v[52:55]
	v_mfma_f32_16x16x32_bf16 v[48:51], v[170:173], v[178:181], v[48:51]
	v_mfma_f32_16x16x32_bf16 v[32:35], v[170:173], v[198:201], v[32:35]
	v_mfma_f32_16x16x32_bf16 v[36:39], v[148:151], v[198:201], v[36:39]
	v_mfma_f32_16x16x32_bf16 v[20:23], v[148:151], v[206:209], v[20:23]
	v_mfma_f32_16x16x32_bf16 v[16:19], v[170:173], v[206:209], v[16:19]
	v_mfma_f32_16x16x32_bf16 v[0:3], v[170:173], v[214:217], v[0:3]
	v_mfma_f32_16x16x32_bf16 v[4:7], v[148:151], v[214:217], v[4:7]
	s_setprio 0
	s_barrier
	s_add_i32 s1, s1, 2
	s_add_u32 s4, s4, 0x100
	s_addc_u32 s5, s5, 0
	s_cmpk_gt_u32 s1, 0x53
	s_mov_b64 s[38:39], s[40:41]
	s_cbranch_scc0 .LBB0_876
	s_and_b64 vcc, exec, s[26:27]
	s_cbranch_vccz .LBB0_879
	s_barrier
